# GEMM residual epilogue (FFN_DOWN/WO): residual-stream loads prefetched (12 up front + 4 refills) instead of 16 load-wait round trips per tile; NA bias lookups batched
# speedup vs baseline: 1.0310x; 1.0102x over previous
; #define LAS __attribute__((address_space(3)))
; template <int DK, int DV, int MODE> ...
;     ...
;       const int ka = ka0 + t;
;       const LAS unsigned char* rp = (const LAS unsigned char*)lut + (ka - ri + 7) * 128;
; #pragma unroll
;       for (int q = 0; q < 8; ++q) { unsigned wv = nacolp[q]; asm volatile("" : "+v"(wv));
; #pragma unroll
;         for (int b4 = 0; b4 < 4; ++b4) { const int j = 4 * q + b4; st[j >> 4][j & 15] += *(const LAS float*)(rp + ((wv >> (8 * b4)) & 0xffu)); } }
;     }
;     float mx = fmaxf(st[0][0], st[1][0]);
; #pragma unroll
;     for (int i = 1; i < 16; ++i) mx = fmaxf(fmaxf(mx, st[0][i]), st[1][i]);
;     mx = fmaxf(mx, __shfl_xor(mx, 32));
;     const float mabs = mx + mbase;
;     if (__any(mabs > mrun + ATT_THR)) {
.LBB0_57:
	s_add_i32 s58, s23, s36
	s_add_i32 s34, s58, -5
	v_cmp_ge_i32_e32 vcc, s34, v225
	v_cmp_lt_i32_e64 s[48:49], s34, v234
	s_and_b64 s[34:35], vcc, s[48:49]
	s_and_saveexec_b64 s[40:41], s[34:35]
	s_cbranch_execz .LBB0_62
	s_mov_b32 s6, 0x1f380
	v_add_u32_sdwa v196, s33, v226 dst_sel:DWORD dst_unused:UNUSED_PAD src0_sel:DWORD src1_sel:BYTE_0
	v_add_u32_sdwa v197, s33, v226 dst_sel:DWORD dst_unused:UNUSED_PAD src0_sel:DWORD src1_sel:BYTE_1
	v_add_u32_sdwa v198, s33, v226 dst_sel:DWORD dst_unused:UNUSED_PAD src0_sel:DWORD src1_sel:BYTE_2
	v_add_u32_sdwa v199, s33, v226 dst_sel:DWORD dst_unused:UNUSED_PAD src0_sel:DWORD src1_sel:BYTE_3
	v_add_u32_sdwa v200, s33, v227 dst_sel:DWORD dst_unused:UNUSED_PAD src0_sel:DWORD src1_sel:BYTE_0
	v_add_u32_sdwa v201, s33, v227 dst_sel:DWORD dst_unused:UNUSED_PAD src0_sel:DWORD src1_sel:BYTE_1
	v_add_u32_sdwa v202, s33, v227 dst_sel:DWORD dst_unused:UNUSED_PAD src0_sel:DWORD src1_sel:BYTE_2
	v_add_u32_sdwa v203, s33, v227 dst_sel:DWORD dst_unused:UNUSED_PAD src0_sel:DWORD src1_sel:BYTE_3
	v_add3_u32 v196, v196, v236, s6
	v_add3_u32 v197, v197, v236, s6
	v_add3_u32 v198, v198, v236, s6
	v_add3_u32 v199, v199, v236, s6
	v_add3_u32 v200, v200, v236, s6
	v_add3_u32 v201, v201, v236, s6
	v_add3_u32 v202, v202, v236, s6
	v_add3_u32 v203, v203, v236, s6
	ds_read_b32 v196, v196
	ds_read_b32 v197, v197
	ds_read_b32 v198, v198
	ds_read_b32 v199, v199
	ds_read_b32 v200, v200
	ds_read_b32 v201, v201
	ds_read_b32 v202, v202
	ds_read_b32 v203, v203
	s_waitcnt lgkmcnt(0)
	v_pk_add_f32 v[114:115], v[114:115], v[196:197]
	v_pk_add_f32 v[116:117], v[116:117], v[198:199]
	v_pk_add_f32 v[118:119], v[118:119], v[200:201]
	v_pk_add_f32 v[120:121], v[120:121], v[202:203]
	v_add_u32_sdwa v196, s33, v228 dst_sel:DWORD dst_unused:UNUSED_PAD src0_sel:DWORD src1_sel:BYTE_0
	v_add_u32_sdwa v197, s33, v228 dst_sel:DWORD dst_unused:UNUSED_PAD src0_sel:DWORD src1_sel:BYTE_1
	v_add_u32_sdwa v198, s33, v228 dst_sel:DWORD dst_unused:UNUSED_PAD src0_sel:DWORD src1_sel:BYTE_2
	v_add_u32_sdwa v199, s33, v228 dst_sel:DWORD dst_unused:UNUSED_PAD src0_sel:DWORD src1_sel:BYTE_3
	v_add_u32_sdwa v200, s33, v229 dst_sel:DWORD dst_unused:UNUSED_PAD src0_sel:DWORD src1_sel:BYTE_0
	v_add_u32_sdwa v201, s33, v229 dst_sel:DWORD dst_unused:UNUSED_PAD src0_sel:DWORD src1_sel:BYTE_1
	v_add_u32_sdwa v202, s33, v229 dst_sel:DWORD dst_unused:UNUSED_PAD src0_sel:DWORD src1_sel:BYTE_2
	v_add_u32_sdwa v203, s33, v229 dst_sel:DWORD dst_unused:UNUSED_PAD src0_sel:DWORD src1_sel:BYTE_3
	v_add3_u32 v196, v196, v236, s6
	v_add3_u32 v197, v197, v236, s6
	v_add3_u32 v198, v198, v236, s6
	v_add3_u32 v199, v199, v236, s6
	v_add3_u32 v200, v200, v236, s6
	v_add3_u32 v201, v201, v236, s6
	v_add3_u32 v202, v202, v236, s6
	v_add3_u32 v203, v203, v236, s6
	ds_read_b32 v196, v196
	ds_read_b32 v197, v197
	ds_read_b32 v198, v198
	ds_read_b32 v199, v199
	ds_read_b32 v200, v200
	ds_read_b32 v201, v201
	ds_read_b32 v202, v202
	ds_read_b32 v203, v203
	s_waitcnt lgkmcnt(0)
	v_pk_add_f32 v[122:123], v[122:123], v[196:197]
	v_pk_add_f32 v[124:125], v[124:125], v[198:199]
	v_pk_add_f32 v[126:127], v[126:127], v[200:201]
	v_pk_add_f32 v[128:129], v[128:129], v[202:203]
	v_add_u32_sdwa v196, s33, v230 dst_sel:DWORD dst_unused:UNUSED_PAD src0_sel:DWORD src1_sel:BYTE_0
	v_add_u32_sdwa v197, s33, v230 dst_sel:DWORD dst_unused:UNUSED_PAD src0_sel:DWORD src1_sel:BYTE_1
	v_add_u32_sdwa v198, s33, v230 dst_sel:DWORD dst_unused:UNUSED_PAD src0_sel:DWORD src1_sel:BYTE_2
	v_add_u32_sdwa v199, s33, v230 dst_sel:DWORD dst_unused:UNUSED_PAD src0_sel:DWORD src1_sel:BYTE_3
	v_add_u32_sdwa v200, s33, v231 dst_sel:DWORD dst_unused:UNUSED_PAD src0_sel:DWORD src1_sel:BYTE_0
	v_add_u32_sdwa v201, s33, v231 dst_sel:DWORD dst_unused:UNUSED_PAD src0_sel:DWORD src1_sel:BYTE_1
	v_add_u32_sdwa v202, s33, v231 dst_sel:DWORD dst_unused:UNUSED_PAD src0_sel:DWORD src1_sel:BYTE_2
	v_add_u32_sdwa v203, s33, v231 dst_sel:DWORD dst_unused:UNUSED_PAD src0_sel:DWORD src1_sel:BYTE_3
	v_add3_u32 v196, v196, v236, s6
	v_add3_u32 v197, v197, v236, s6
	v_add3_u32 v198, v198, v236, s6
	v_add3_u32 v199, v199, v236, s6
	v_add3_u32 v200, v200, v236, s6
	v_add3_u32 v201, v201, v236, s6
	v_add3_u32 v202, v202, v236, s6
	v_add3_u32 v203, v203, v236, s6
	ds_read_b32 v196, v196
	ds_read_b32 v197, v197
	ds_read_b32 v198, v198
	ds_read_b32 v199, v199
	ds_read_b32 v200, v200
	ds_read_b32 v201, v201
	ds_read_b32 v202, v202
	ds_read_b32 v203, v203
	s_waitcnt lgkmcnt(0)
	v_pk_add_f32 v[98:99], v[98:99], v[196:197]
	v_pk_add_f32 v[100:101], v[100:101], v[198:199]
	v_pk_add_f32 v[102:103], v[102:103], v[200:201]
	v_pk_add_f32 v[104:105], v[104:105], v[202:203]
	v_add_u32_sdwa v196, s33, v232 dst_sel:DWORD dst_unused:UNUSED_PAD src0_sel:DWORD src1_sel:BYTE_0
	v_add_u32_sdwa v197, s33, v232 dst_sel:DWORD dst_unused:UNUSED_PAD src0_sel:DWORD src1_sel:BYTE_1
	v_add_u32_sdwa v198, s33, v232 dst_sel:DWORD dst_unused:UNUSED_PAD src0_sel:DWORD src1_sel:BYTE_2
	v_add_u32_sdwa v199, s33, v232 dst_sel:DWORD dst_unused:UNUSED_PAD src0_sel:DWORD src1_sel:BYTE_3
	v_add_u32_sdwa v200, s33, v233 dst_sel:DWORD dst_unused:UNUSED_PAD src0_sel:DWORD src1_sel:BYTE_0
	v_add_u32_sdwa v201, s33, v233 dst_sel:DWORD dst_unused:UNUSED_PAD src0_sel:DWORD src1_sel:BYTE_1
	v_add_u32_sdwa v202, s33, v233 dst_sel:DWORD dst_unused:UNUSED_PAD src0_sel:DWORD src1_sel:BYTE_2
	v_add_u32_sdwa v203, s33, v233 dst_sel:DWORD dst_unused:UNUSED_PAD src0_sel:DWORD src1_sel:BYTE_3
	v_add3_u32 v196, v196, v236, s6
	v_add3_u32 v197, v197, v236, s6
	v_add3_u32 v198, v198, v236, s6
	v_add3_u32 v199, v199, v236, s6
	v_add3_u32 v200, v200, v236, s6
	v_add3_u32 v201, v201, v236, s6
	v_add3_u32 v202, v202, v236, s6
	v_add3_u32 v203, v203, v236, s6
	ds_read_b32 v196, v196
	ds_read_b32 v197, v197
	ds_read_b32 v198, v198
	ds_read_b32 v199, v199
	ds_read_b32 v200, v200
	ds_read_b32 v201, v201
	ds_read_b32 v202, v202
	ds_read_b32 v203, v203
	s_waitcnt lgkmcnt(0)
	v_pk_add_f32 v[106:107], v[106:107], v[196:197]
	v_pk_add_f32 v[108:109], v[108:109], v[198:199]
	v_pk_add_f32 v[110:111], v[110:111], v[200:201]
	v_pk_add_f32 v[112:113], v[112:113], v[202:203]
	v_max_f32_e32 v0, v114, v98
	v_max3_f32 v0, v0, v115, v99
	v_max3_f32 v0, v0, v116, v100
	v_max3_f32 v0, v0, v117, v101
	v_max3_f32 v0, v0, v118, v102
	v_max3_f32 v0, v0, v119, v103
	v_max3_f32 v0, v0, v120, v104
	v_max3_f32 v0, v0, v121, v105
	v_max3_f32 v0, v0, v122, v106
	v_max3_f32 v0, v0, v123, v107
	v_max3_f32 v0, v0, v124, v108
	v_max3_f32 v0, v0, v125, v109
	v_and_b32_e32 v3, 64, v221
	v_max3_f32 v0, v0, v126, v110
	v_xor_b32_e32 v2, 32, v221
	v_add_u32_e32 v3, 64, v3
	v_max3_f32 v0, v0, v127, v111
	v_cmp_lt_i32_e32 vcc, v2, v3
	v_max3_f32 v0, v0, v128, v112
	v_max3_f32 v0, v0, v129, v113
	v_cndmask_b32_e32 v2, v221, v2, vcc
	v_lshlrev_b32_e32 v2, 2, v2
	ds_bpermute_b32 v2, v2, v0
	s_waitcnt lgkmcnt(0)
	v_max_f32_e32 v2, v2, v2
	v_max_f32_e32 v174, v0, v2
	v_pk_add_f32 v[2:3], v[192:193], v[174:175]
	s_nop 0
	v_cmp_gt_f32_e32 vcc, v2, v3
	s_cbranch_vccz .LBB0_60
; DI float fexp2(float x) { return __builtin_amdgcn_exp2f(x); }
; template <int DK, int DV, int MODE> ...
;     ...
;     if (__any(mabs > mrun + ATT_THR)) {
;       const float mn = fmaxf(mrun, mabs), alpha = fexp2(mrun - mn); mrun = mn; lsum *= alpha;
; #pragma unroll
;       for (int db = 0; db < DV / 32; ++db)
; #pragma unroll
;         for (int i = 0; i < 16; ++i) O[db][i] *= alpha;
;     }
	v_max_f32_e32 v0, v2, v2
	v_max_f32_e32 v2, v193, v193
	v_max_f32_e32 v2, v2, v0
	v_sub_f32_e32 v0, v193, v2
	v_exp_f32_e32 v0, v0
	v_mov_b32_e32 v193, v2
	v_mul_f32_e32 v32, v32, v0
	v_pk_mul_f32 v[64:65], v[64:65], v[0:1] op_sel_hi:[1,0]
	v_pk_mul_f32 v[62:63], v[62:63], v[0:1] op_sel_hi:[1,0]
	v_pk_mul_f32 v[60:61], v[60:61], v[0:1] op_sel_hi:[1,0]
	v_pk_mul_f32 v[58:59], v[58:59], v[0:1] op_sel_hi:[1,0]
	v_pk_mul_f32 v[56:57], v[56:57], v[0:1] op_sel_hi:[1,0]
	v_pk_mul_f32 v[54:55], v[54:55], v[0:1] op_sel_hi:[1,0]
	v_pk_mul_f32 v[52:53], v[52:53], v[0:1] op_sel_hi:[1,0]
	v_pk_mul_f32 v[50:51], v[50:51], v[0:1] op_sel_hi:[1,0]
	v_pk_mul_f32 v[48:49], v[48:49], v[0:1] op_sel_hi:[1,0]
	v_pk_mul_f32 v[46:47], v[46:47], v[0:1] op_sel_hi:[1,0]
	v_pk_mul_f32 v[44:45], v[44:45], v[0:1] op_sel_hi:[1,0]
	v_pk_mul_f32 v[42:43], v[42:43], v[0:1] op_sel_hi:[1,0]
	v_pk_mul_f32 v[40:41], v[40:41], v[0:1] op_sel_hi:[1,0]
	v_pk_mul_f32 v[38:39], v[38:39], v[0:1] op_sel_hi:[1,0]
	v_pk_mul_f32 v[36:37], v[36:37], v[0:1] op_sel_hi:[1,0]
	v_pk_mul_f32 v[34:35], v[34:35], v[0:1] op_sel_hi:[1,0]

; #define LAS __attribute__((address_space(3)))
; template <int DK, int DV, int MODE> ...
;     ...
;       const int ka = ka0 + t;
;       const LAS unsigned char* rp = (const LAS unsigned char*)lut + (ka - ri + 7) * 128;
; #pragma unroll
;       for (int q = 0; q < 8; ++q) { unsigned wv = nacolp[q]; asm volatile("" : "+v"(wv));
; #pragma unroll
;         for (int b4 = 0; b4 < 4; ++b4) { const int j = 4 * q + b4; st[j >> 4][j & 15] += *(const LAS float*)(rp + ((wv >> (8 * b4)) & 0xffu)); } }
;     }
;     float mx = fmaxf(st[0][0], st[1][0]);
; #pragma unroll
;     for (int i = 1; i < 16; ++i) mx = fmaxf(fmaxf(mx, st[0][i]), st[1][i]);
;     mx = fmaxf(mx, __shfl_xor(mx, 32));
;     const float mabs = mx + mbase;
;     if (__any(mabs > mrun + ATT_THR)) {
.LBB0_81:
	s_add_i32 s58, s58, -4
	v_cmp_ge_i32_e32 vcc, s58, v225
	v_cmp_lt_i32_e64 s[46:47], s58, v234
	s_and_b64 s[26:27], vcc, s[46:47]
	s_and_saveexec_b64 s[28:29], s[26:27]
	s_cbranch_execz .LBB0_86
	s_mov_b32 s6, 0x1f400
	v_mov_b32_e32 v31, v193
	v_add_u32_sdwa v196, s33, v226 dst_sel:DWORD dst_unused:UNUSED_PAD src0_sel:DWORD src1_sel:BYTE_0
	v_add_u32_sdwa v197, s33, v226 dst_sel:DWORD dst_unused:UNUSED_PAD src0_sel:DWORD src1_sel:BYTE_1
	v_add_u32_sdwa v198, s33, v226 dst_sel:DWORD dst_unused:UNUSED_PAD src0_sel:DWORD src1_sel:BYTE_2
	v_add_u32_sdwa v199, s33, v226 dst_sel:DWORD dst_unused:UNUSED_PAD src0_sel:DWORD src1_sel:BYTE_3
	v_add_u32_sdwa v200, s33, v227 dst_sel:DWORD dst_unused:UNUSED_PAD src0_sel:DWORD src1_sel:BYTE_0
	v_add_u32_sdwa v201, s33, v227 dst_sel:DWORD dst_unused:UNUSED_PAD src0_sel:DWORD src1_sel:BYTE_1
	v_add_u32_sdwa v202, s33, v227 dst_sel:DWORD dst_unused:UNUSED_PAD src0_sel:DWORD src1_sel:BYTE_2
	v_add_u32_sdwa v203, s33, v227 dst_sel:DWORD dst_unused:UNUSED_PAD src0_sel:DWORD src1_sel:BYTE_3
	v_add3_u32 v196, v196, v236, s6
	v_add3_u32 v197, v197, v236, s6
	v_add3_u32 v198, v198, v236, s6
	v_add3_u32 v199, v199, v236, s6
	v_add3_u32 v200, v200, v236, s6
	v_add3_u32 v201, v201, v236, s6
	v_add3_u32 v202, v202, v236, s6
	v_add3_u32 v203, v203, v236, s6
	ds_read_b32 v196, v196
	ds_read_b32 v197, v197
	ds_read_b32 v198, v198
	ds_read_b32 v199, v199
	ds_read_b32 v200, v200
	ds_read_b32 v201, v201
	ds_read_b32 v202, v202
	ds_read_b32 v203, v203
	s_waitcnt lgkmcnt(0)
	v_pk_add_f32 v[130:131], v[130:131], v[196:197]
	v_pk_add_f32 v[132:133], v[132:133], v[198:199]
	v_pk_add_f32 v[134:135], v[134:135], v[200:201]
	v_pk_add_f32 v[136:137], v[136:137], v[202:203]
	v_add_u32_sdwa v196, s33, v228 dst_sel:DWORD dst_unused:UNUSED_PAD src0_sel:DWORD src1_sel:BYTE_0
	v_add_u32_sdwa v197, s33, v228 dst_sel:DWORD dst_unused:UNUSED_PAD src0_sel:DWORD src1_sel:BYTE_1
	v_add_u32_sdwa v198, s33, v228 dst_sel:DWORD dst_unused:UNUSED_PAD src0_sel:DWORD src1_sel:BYTE_2
	v_add_u32_sdwa v199, s33, v228 dst_sel:DWORD dst_unused:UNUSED_PAD src0_sel:DWORD src1_sel:BYTE_3
	v_add_u32_sdwa v200, s33, v229 dst_sel:DWORD dst_unused:UNUSED_PAD src0_sel:DWORD src1_sel:BYTE_0
	v_add_u32_sdwa v201, s33, v229 dst_sel:DWORD dst_unused:UNUSED_PAD src0_sel:DWORD src1_sel:BYTE_1
	v_add_u32_sdwa v202, s33, v229 dst_sel:DWORD dst_unused:UNUSED_PAD src0_sel:DWORD src1_sel:BYTE_2
	v_add_u32_sdwa v203, s33, v229 dst_sel:DWORD dst_unused:UNUSED_PAD src0_sel:DWORD src1_sel:BYTE_3
	v_add3_u32 v196, v196, v236, s6
	v_add3_u32 v197, v197, v236, s6
	v_add3_u32 v198, v198, v236, s6
	v_add3_u32 v199, v199, v236, s6
	v_add3_u32 v200, v200, v236, s6
	v_add3_u32 v201, v201, v236, s6
	v_add3_u32 v202, v202, v236, s6
	v_add3_u32 v203, v203, v236, s6
	ds_read_b32 v196, v196
	ds_read_b32 v197, v197
	ds_read_b32 v198, v198
	ds_read_b32 v199, v199
	ds_read_b32 v200, v200
	ds_read_b32 v201, v201
	ds_read_b32 v202, v202
	ds_read_b32 v203, v203
	s_waitcnt lgkmcnt(0)
	v_pk_add_f32 v[138:139], v[138:139], v[196:197]
	v_pk_add_f32 v[140:141], v[140:141], v[198:199]
	v_pk_add_f32 v[142:143], v[142:143], v[200:201]
	v_pk_add_f32 v[144:145], v[144:145], v[202:203]
	v_add_u32_sdwa v196, s33, v230 dst_sel:DWORD dst_unused:UNUSED_PAD src0_sel:DWORD src1_sel:BYTE_0
	v_add_u32_sdwa v197, s33, v230 dst_sel:DWORD dst_unused:UNUSED_PAD src0_sel:DWORD src1_sel:BYTE_1
	v_add_u32_sdwa v198, s33, v230 dst_sel:DWORD dst_unused:UNUSED_PAD src0_sel:DWORD src1_sel:BYTE_2
	v_add_u32_sdwa v199, s33, v230 dst_sel:DWORD dst_unused:UNUSED_PAD src0_sel:DWORD src1_sel:BYTE_3
	v_add_u32_sdwa v200, s33, v231 dst_sel:DWORD dst_unused:UNUSED_PAD src0_sel:DWORD src1_sel:BYTE_0
	v_add_u32_sdwa v201, s33, v231 dst_sel:DWORD dst_unused:UNUSED_PAD src0_sel:DWORD src1_sel:BYTE_1
	v_add_u32_sdwa v202, s33, v231 dst_sel:DWORD dst_unused:UNUSED_PAD src0_sel:DWORD src1_sel:BYTE_2
	v_add_u32_sdwa v203, s33, v231 dst_sel:DWORD dst_unused:UNUSED_PAD src0_sel:DWORD src1_sel:BYTE_3
	v_add3_u32 v196, v196, v236, s6
	v_add3_u32 v197, v197, v236, s6
	v_add3_u32 v198, v198, v236, s6
	v_add3_u32 v199, v199, v236, s6
	v_add3_u32 v200, v200, v236, s6
	v_add3_u32 v201, v201, v236, s6
	v_add3_u32 v202, v202, v236, s6
	v_add3_u32 v203, v203, v236, s6
	ds_read_b32 v196, v196
	ds_read_b32 v197, v197
	ds_read_b32 v198, v198
	ds_read_b32 v199, v199
	ds_read_b32 v200, v200
	ds_read_b32 v201, v201
	ds_read_b32 v202, v202
	ds_read_b32 v203, v203
	s_waitcnt lgkmcnt(0)
	v_pk_add_f32 v[2:3], v[2:3], v[196:197]
	v_pk_add_f32 v[4:5], v[4:5], v[198:199]
	v_pk_add_f32 v[6:7], v[6:7], v[200:201]
	v_pk_add_f32 v[8:9], v[8:9], v[202:203]
	v_add_u32_sdwa v196, s33, v232 dst_sel:DWORD dst_unused:UNUSED_PAD src0_sel:DWORD src1_sel:BYTE_0
	v_add_u32_sdwa v197, s33, v232 dst_sel:DWORD dst_unused:UNUSED_PAD src0_sel:DWORD src1_sel:BYTE_1
	v_add_u32_sdwa v198, s33, v232 dst_sel:DWORD dst_unused:UNUSED_PAD src0_sel:DWORD src1_sel:BYTE_2
	v_add_u32_sdwa v199, s33, v232 dst_sel:DWORD dst_unused:UNUSED_PAD src0_sel:DWORD src1_sel:BYTE_3
	v_add_u32_sdwa v200, s33, v233 dst_sel:DWORD dst_unused:UNUSED_PAD src0_sel:DWORD src1_sel:BYTE_0
	v_add_u32_sdwa v201, s33, v233 dst_sel:DWORD dst_unused:UNUSED_PAD src0_sel:DWORD src1_sel:BYTE_1
	v_add_u32_sdwa v202, s33, v233 dst_sel:DWORD dst_unused:UNUSED_PAD src0_sel:DWORD src1_sel:BYTE_2
	v_add_u32_sdwa v203, s33, v233 dst_sel:DWORD dst_unused:UNUSED_PAD src0_sel:DWORD src1_sel:BYTE_3
	v_add3_u32 v196, v196, v236, s6
	v_add3_u32 v197, v197, v236, s6
	v_add3_u32 v198, v198, v236, s6
	v_add3_u32 v199, v199, v236, s6
	v_add3_u32 v200, v200, v236, s6
	v_add3_u32 v201, v201, v236, s6
	v_add3_u32 v202, v202, v236, s6
	v_add3_u32 v203, v203, v236, s6
	ds_read_b32 v196, v196
	ds_read_b32 v197, v197
	ds_read_b32 v198, v198
	ds_read_b32 v199, v199
	ds_read_b32 v200, v200
	ds_read_b32 v201, v201
	ds_read_b32 v202, v202
	ds_read_b32 v203, v203
	s_waitcnt lgkmcnt(0)
	v_pk_add_f32 v[10:11], v[10:11], v[196:197]
	v_pk_add_f32 v[12:13], v[12:13], v[198:199]
	v_pk_add_f32 v[14:15], v[14:15], v[200:201]
	v_pk_add_f32 v[16:17], v[16:17], v[202:203]
	v_max_f32_e32 v0, v130, v2
	v_max3_f32 v0, v0, v131, v3
	v_max3_f32 v0, v0, v132, v4
	v_max3_f32 v0, v0, v133, v5
	v_max3_f32 v0, v0, v134, v6
	v_max3_f32 v0, v0, v135, v7
	v_max3_f32 v0, v0, v136, v8
	v_max3_f32 v0, v0, v137, v9
	v_max3_f32 v0, v0, v138, v10
	v_max3_f32 v0, v0, v139, v11
	v_max3_f32 v0, v0, v140, v12
	v_max3_f32 v0, v0, v141, v13
	v_and_b32_e32 v19, 64, v221
	v_max3_f32 v0, v0, v142, v14
	v_xor_b32_e32 v18, 32, v221
	v_add_u32_e32 v19, 64, v19
	v_max3_f32 v0, v0, v143, v15
	v_cmp_lt_i32_e32 vcc, v18, v19
	v_max3_f32 v0, v0, v144, v16
	v_max3_f32 v0, v0, v145, v17
	v_cndmask_b32_e32 v18, v221, v18, vcc
	v_lshlrev_b32_e32 v18, 2, v18
	ds_bpermute_b32 v18, v18, v0
	s_waitcnt lgkmcnt(0)
	v_max_f32_e32 v18, v18, v18
	v_max_f32_e32 v174, v0, v18
	v_pk_add_f32 v[18:19], v[30:31], v[174:175]
	s_nop 0
	v_cmp_gt_f32_e32 vcc, v18, v19
	s_cbranch_vccz .LBB0_84
; DI float fexp2(float x) { return __builtin_amdgcn_exp2f(x); }
; template <int DK, int DV, int MODE> ...
;     ...
;     if (__any(mabs > mrun + ATT_THR)) {
;       const float mn = fmaxf(mrun, mabs), alpha = fexp2(mrun - mn); mrun = mn; lsum *= alpha;
; #pragma unroll
;       for (int db = 0; db < DV / 32; ++db)
; #pragma unroll
;         for (int i = 0; i < 16; ++i) O[db][i] *= alpha;
;     }
	v_max_f32_e32 v0, v18, v18
	v_max_f32_e32 v18, v193, v193
	v_max_f32_e32 v18, v18, v0
	v_sub_f32_e32 v0, v193, v18
	v_exp_f32_e32 v0, v0
	v_mov_b32_e32 v193, v18
	v_mul_f32_e32 v32, v32, v0
	v_pk_mul_f32 v[64:65], v[64:65], v[0:1] op_sel_hi:[1,0]
	v_pk_mul_f32 v[62:63], v[62:63], v[0:1] op_sel_hi:[1,0]
	v_pk_mul_f32 v[60:61], v[60:61], v[0:1] op_sel_hi:[1,0]
	v_pk_mul_f32 v[58:59], v[58:59], v[0:1] op_sel_hi:[1,0]
	v_pk_mul_f32 v[56:57], v[56:57], v[0:1] op_sel_hi:[1,0]
	v_pk_mul_f32 v[54:55], v[54:55], v[0:1] op_sel_hi:[1,0]
	v_pk_mul_f32 v[52:53], v[52:53], v[0:1] op_sel_hi:[1,0]
	v_pk_mul_f32 v[50:51], v[50:51], v[0:1] op_sel_hi:[1,0]
	v_pk_mul_f32 v[48:49], v[48:49], v[0:1] op_sel_hi:[1,0]
	v_pk_mul_f32 v[46:47], v[46:47], v[0:1] op_sel_hi:[1,0]
	v_pk_mul_f32 v[44:45], v[44:45], v[0:1] op_sel_hi:[1,0]
	v_pk_mul_f32 v[42:43], v[42:43], v[0:1] op_sel_hi:[1,0]
	v_pk_mul_f32 v[40:41], v[40:41], v[0:1] op_sel_hi:[1,0]
	v_pk_mul_f32 v[38:39], v[38:39], v[0:1] op_sel_hi:[1,0]
	v_pk_mul_f32 v[36:37], v[36:37], v[0:1] op_sel_hi:[1,0]
	v_pk_mul_f32 v[34:35], v[34:35], v[0:1] op_sel_hi:[1,0]

; #define LAS __attribute__((address_space(3)))
; DI u32x2 pk4(f32x4 v) { u32x2 r; r.x = cvt_pk(v[0], v[1]); r.y = cvt_pk(v[2], v[3]); return r; }
; DI void gemm_phase(LAS unsigned char* lds, const GemmDesc& d, float* __restrict__ X) {
;     ...
;       LAS float* red = (LAS float*)(lds + 133120); const float alpha = d.K == FF ? 0.5f : 1.f;
; #pragma unroll
;       for (int ai = 0; ai < 2; ++ai)
; #pragma unroll
;         for (int m = 0; m < 4; ++m) {
;           const int row = pm * 256 + 128 * ai + 16 * m + rb; float ss = 0.f;
; #pragma unroll
;           for (int bj = 0; bj < 2; ++bj) {
;             const size_t o = (size_t)row * DM + pn * 256 + 128 * bj + cb;
;             const u32x4 xw = *(const u32x4*)(d.O0 + o); u32x4 ow;
; #pragma unroll
;             for (int n = 0; n < 2; ++n) {
;               const unsigned w0 = n ? xw.z : xw.x, w1 = n ? xw.w : xw.y;
;               f32x4 xo; xo[0] = __uint_as_float(w0 << 16); xo[1] = __uint_as_float(w0 & 0xffff0000u); xo[2] = __uint_as_float(w1 << 16); xo[3] = __uint_as_float(w1 & 0xffff0000u);
;               const f32x4 xn = xo + acc[ai][bj][m][n] * alpha;
;               ss += (xn[0] * xn[0] + xn[1] * xn[1]) + (xn[2] * xn[2] + xn[3] * xn[3]);
;               const u32x2 pw = pk4(xn); if (n) { ow.z = pw.x; ow.w = pw.y; } else { ow.x = pw.x; ow.y = pw.y; }
;             }
;             *(u32x4*)(d.O0 + o) = ow;
;           }
;           ss += __shfl_xor(ss, 16); ss += __shfl_xor(ss, 32);
;           if (fq == 0) red[wc * 256 + 128 * ai + 16 * m + rb] = ss;
.LBB0_522:
	s_andn2_b64 vcc, exec, s[44:45]
	s_cbranch_vccnz .LBB0_542
	s_lshl_b32 s46, s97, 8
	s_lshl_b32 s6, s68, 8
	s_waitcnt vmcnt(0)
	v_add_u32_e32 v132, s46, v163
	s_ashr_i32 s14, s6, 31
	s_waitcnt lgkmcnt(0)
	v_or_b32_e32 v130, s6, v182
	v_mov_b32_e32 v131, s14
	v_ashrrev_i32_e32 v133, 31, v132
	v_lshl_add_u64 v[134:135], v[130:131], 1, s[28:29]
	v_lshlrev_b64 v[136:137], 11, v[132:133]
	v_lshl_add_u64 v[138:139], v[134:135], 0, v[136:137]
	v_lshlrev_b32_e32 v243, 11, v132
	v_lshl_add_u32 v243, v130, 1, v243
	global_load_dwordx4 v[142:145], v243, s[28:29]
	global_load_dwordx4 v[166:169], v243, s[28:29] offset:256
	v_add_u32_e32 v252, 0x8000, v243
	global_load_dwordx4 v[170:173], v252, s[28:29]
	v_add_u32_e32 v252, 0x8000, v243
	global_load_dwordx4 v[184:187], v252, s[28:29] offset:256
	v_add_u32_e32 v252, 0x10000, v243
	global_load_dwordx4 v[188:191], v252, s[28:29]
	v_add_u32_e32 v252, 0x10000, v243
	global_load_dwordx4 v[216:219], v252, s[28:29] offset:256
	v_add_u32_e32 v252, 0x18000, v243
	global_load_dwordx4 v[222:225], v252, s[28:29]
	v_add_u32_e32 v252, 0x18000, v243
	global_load_dwordx4 v[226:229], v252, s[28:29] offset:256
	v_add_u32_e32 v252, 0x40000, v243
	global_load_dwordx4 v[230:233], v252, s[28:29]
	v_add_u32_e32 v252, 0x40000, v243
	global_load_dwordx4 v[234:237], v252, s[28:29] offset:256
	v_add_u32_e32 v252, 0x48000, v243
	global_load_dwordx4 v[244:247], v252, s[28:29]
	v_add_u32_e32 v252, 0x48000, v243
	global_load_dwordx4 v[248:251], v252, s[28:29] offset:256
	s_waitcnt vmcnt(11)
	v_mov_b32_e32 v134, v142
	v_mov_b32_e32 v135, v143
	v_mov_b32_e32 v136, v144
	v_mov_b32_e32 v137, v145
	v_add_u32_e32 v252, 0x50000, v243
	global_load_dwordx4 v[142:145], v252, s[28:29]
	s_lshl_b32 s6, s20, 10
	s_add_i32 s6, s6, 0
	s_add_i32 s6, s6, 0x20800
	v_cmp_eq_u32_e32 vcc, 0, v179
	v_lshl_add_u32 v0, v163, 2, s6
	s_nop 0
	v_lshlrev_b32_e32 v140, 16, v134
	v_and_b32_e32 v141, 0xffff0000, v134
	v_lshlrev_b32_e32 v134, 16, v135
	v_and_b32_e32 v135, 0xffff0000, v135
	v_pk_fma_f32 v[128:129], s[66:67], v[128:129], v[134:135]
	v_pk_fma_f32 v[126:127], s[60:61], v[126:127], v[140:141]
	v_mul_f32_e32 v134, v129, v129
	v_mul_f32_e32 v133, v127, v127
	v_fmac_f32_e32 v133, v126, v126
	v_fmac_f32_e32 v134, v128, v128
	v_add_f32_e32 v133, v133, v134
	v_cvt_pk_bf16_f32 v126, v126, v127
	v_cvt_pk_bf16_f32 v127, v128, v129
	v_lshlrev_b32_e32 v128, 16, v136
	v_and_b32_e32 v129, 0xffff0000, v136
	v_lshlrev_b32_e32 v134, 16, v137
	v_and_b32_e32 v135, 0xffff0000, v137
	v_pk_fma_f32 v[124:125], s[66:67], v[124:125], v[134:135]
	v_pk_fma_f32 v[122:123], s[60:61], v[122:123], v[128:129]
	v_mul_f32_e32 v129, v125, v125
	v_mul_f32_e32 v128, v123, v123
	v_fmac_f32_e32 v128, v122, v122
	v_fmac_f32_e32 v129, v124, v124
	v_add_f32_e32 v128, v128, v129
	v_add_f32_e32 v133, v133, v128
	v_cvt_pk_bf16_f32 v128, v122, v123
	v_cvt_pk_bf16_f32 v129, v124, v125
	s_waitcnt vmcnt(11)
	v_mov_b32_e32 v122, v166
	v_mov_b32_e32 v123, v167
	v_mov_b32_e32 v124, v168
	v_mov_b32_e32 v125, v169
	v_add_u32_e32 v252, 0x50000, v243
	global_load_dwordx4 v[166:169], v252, s[28:29] offset:256
	s_nop 0
	global_store_dwordx4 v[138:139], v[126:129], off
	s_nop 0
	s_nop 0
	v_lshlrev_b32_e32 v126, 16, v122
	v_and_b32_e32 v127, 0xffff0000, v122
	v_lshlrev_b32_e32 v122, 16, v123
	v_and_b32_e32 v123, 0xffff0000, v123
	v_pk_fma_f32 v[120:121], s[66:67], v[120:121], v[122:123]
	v_pk_fma_f32 v[118:119], s[60:61], v[118:119], v[126:127]
	v_mul_f32_e32 v123, v121, v121
	v_mul_f32_e32 v122, v119, v119
	v_fmac_f32_e32 v122, v118, v118
	v_fmac_f32_e32 v123, v120, v120
	v_add_f32_e32 v122, v122, v123
	v_add_f32_e32 v126, v133, v122
	v_cvt_pk_bf16_f32 v118, v118, v119
	v_cvt_pk_bf16_f32 v119, v120, v121
	v_lshlrev_b32_e32 v120, 16, v124
	v_and_b32_e32 v121, 0xffff0000, v124
	v_lshlrev_b32_e32 v122, 16, v125
	v_and_b32_e32 v123, 0xffff0000, v125
	v_pk_fma_f32 v[116:117], s[66:67], v[116:117], v[122:123]
	v_pk_fma_f32 v[114:115], s[60:61], v[114:115], v[120:121]
	v_mul_f32_e32 v121, v117, v117
	v_mul_f32_e32 v120, v115, v115
	v_fmac_f32_e32 v120, v114, v114
	v_fmac_f32_e32 v121, v116, v116
	v_add_f32_e32 v120, v120, v121
	v_add_f32_e32 v122, v120, v126
	v_cvt_pk_bf16_f32 v120, v114, v115
	v_and_b32_e32 v115, 64, v221
	v_xor_b32_e32 v114, 16, v221
	v_add_u32_e32 v115, 64, v115
	v_cmp_lt_i32_e64 s[44:45], v114, v115
	v_cvt_pk_bf16_f32 v121, v116, v117
	v_xor_b32_e32 v117, 32, v221
	global_store_dwordx4 v[138:139], v[118:121], off offset:256
	v_cndmask_b32_e64 v114, v221, v114, s[44:45]
	v_lshlrev_b32_e32 v116, 2, v114
	ds_bpermute_b32 v114, v116, v122
	v_cmp_lt_i32_e64 s[44:45], v117, v115
	s_waitcnt lgkmcnt(0)
	v_add_f32_e32 v114, v122, v114
	v_cndmask_b32_e64 v115, v221, v117, s[44:45]
	v_lshlrev_b32_e32 v117, 2, v115
	ds_bpermute_b32 v115, v117, v114
	s_and_saveexec_b64 s[44:45], vcc
	s_cbranch_execz .LBB0_525
	s_waitcnt lgkmcnt(0)
	v_add_f32_e32 v114, v114, v115
	ds_write_b32 v0, v114
; DI u32x2 pk4(f32x4 v) { u32x2 r; r.x = cvt_pk(v[0], v[1]); r.y = cvt_pk(v[2], v[3]); return r; }
; DI void gemm_phase(LAS unsigned char* lds, const GemmDesc& d, float* __restrict__ X) {
;     ...
;           const int row = pm * 256 + 128 * ai + 16 * m + rb; float ss = 0.f;
; #pragma unroll
;           for (int bj = 0; bj < 2; ++bj) {
;             const size_t o = (size_t)row * DM + pn * 256 + 128 * bj + cb;
;             const u32x4 xw = *(const u32x4*)(d.O0 + o); u32x4 ow;
; #pragma unroll
;             for (int n = 0; n < 2; ++n) {
;               const unsigned w0 = n ? xw.z : xw.x, w1 = n ? xw.w : xw.y;
;               f32x4 xo; xo[0] = __uint_as_float(w0 << 16); xo[1] = __uint_as_float(w0 & 0xffff0000u); xo[2] = __uint_as_float(w1 << 16); xo[3] = __uint_as_float(w1 & 0xffff0000u);
;               const f32x4 xn = xo + acc[ai][bj][m][n] * alpha;
;               ss += (xn[0] * xn[0] + xn[1] * xn[1]) + (xn[2] * xn[2] + xn[3] * xn[3]);
;               const u32x2 pw = pk4(xn); if (n) { ow.z = pw.x; ow.w = pw.y; } else { ow.x = pw.x; ow.y = pw.y; }
;             }
;             *(u32x4*)(d.O0 + o) = ow;
;           }
;           ss += __shfl_xor(ss, 16); ss += __shfl_xor(ss, 32);
;           if (fq == 0) red[wc * 256 + 128 * ai + 16 * m + rb] = ss;
.LBB0_525:
	s_or_b64 exec, exec, s[44:45]
	v_or_b32_e32 v114, 16, v132
	s_waitcnt lgkmcnt(0)
	v_ashrrev_i32_e32 v115, 31, v114
	v_lshlrev_b64 v[114:115], 11, v[114:115]
	v_lshl_add_u64 v[114:115], s[28:29], 0, v[114:115]
	v_lshl_add_u64 v[114:115], v[130:131], 1, v[114:115]
	s_waitcnt vmcnt(13)
	v_mov_b32_e32 v118, v170
	v_mov_b32_e32 v119, v171
	v_mov_b32_e32 v120, v172
	v_mov_b32_e32 v121, v173
	v_add_u32_e32 v252, 0x58000, v243
	global_load_dwordx4 v[170:173], v252, s[28:29]
	s_nop 0
	v_lshlrev_b32_e32 v122, 16, v118
	v_and_b32_e32 v123, 0xffff0000, v118
	v_lshlrev_b32_e32 v118, 16, v119
	v_and_b32_e32 v119, 0xffff0000, v119
	v_pk_fma_f32 v[112:113], s[66:67], v[112:113], v[118:119]
	v_pk_fma_f32 v[110:111], s[60:61], v[110:111], v[122:123]
	v_mul_f32_e32 v119, v113, v113
	v_mul_f32_e32 v118, v111, v111
	v_fmac_f32_e32 v118, v110, v110
	v_fmac_f32_e32 v119, v112, v112
	v_add_f32_e32 v122, v118, v119
	v_cvt_pk_bf16_f32 v110, v110, v111
	v_cvt_pk_bf16_f32 v111, v112, v113
	v_lshlrev_b32_e32 v112, 16, v120
	v_and_b32_e32 v113, 0xffff0000, v120
	v_lshlrev_b32_e32 v118, 16, v121
	v_and_b32_e32 v119, 0xffff0000, v121
	v_pk_fma_f32 v[108:109], s[66:67], v[108:109], v[118:119]
	v_pk_fma_f32 v[106:107], s[60:61], v[106:107], v[112:113]
	v_mul_f32_e32 v113, v109, v109
	v_mul_f32_e32 v112, v107, v107
	v_fmac_f32_e32 v112, v106, v106
	v_fmac_f32_e32 v113, v108, v108
	v_add_f32_e32 v112, v112, v113
	v_add_f32_e32 v118, v122, v112
	v_cvt_pk_bf16_f32 v112, v106, v107
	v_cvt_pk_bf16_f32 v113, v108, v109
	s_waitcnt vmcnt(13)
	v_mov_b32_e32 v106, v184
	v_mov_b32_e32 v107, v185
	v_mov_b32_e32 v108, v186
	v_mov_b32_e32 v109, v187
	v_add_u32_e32 v252, 0x58000, v243
	global_load_dwordx4 v[184:187], v252, s[28:29] offset:256
	s_nop 0
	global_store_dwordx4 v[114:115], v[110:113], off
	s_nop 0
	s_nop 0
	v_lshlrev_b32_e32 v110, 16, v106
	v_and_b32_e32 v111, 0xffff0000, v106
	v_lshlrev_b32_e32 v106, 16, v107
	v_and_b32_e32 v107, 0xffff0000, v107
	v_pk_fma_f32 v[104:105], s[66:67], v[104:105], v[106:107]
	v_pk_fma_f32 v[102:103], s[60:61], v[102:103], v[110:111]
	v_mul_f32_e32 v107, v105, v105
	v_mul_f32_e32 v106, v103, v103
	v_fmac_f32_e32 v106, v102, v102
	v_fmac_f32_e32 v107, v104, v104
	v_add_f32_e32 v106, v106, v107
	v_add_f32_e32 v110, v118, v106
	v_cvt_pk_bf16_f32 v102, v102, v103
	v_cvt_pk_bf16_f32 v103, v104, v105
	v_lshlrev_b32_e32 v104, 16, v108
	v_and_b32_e32 v105, 0xffff0000, v108
	v_lshlrev_b32_e32 v106, 16, v109
	v_and_b32_e32 v107, 0xffff0000, v109
	v_pk_fma_f32 v[100:101], s[66:67], v[100:101], v[106:107]
	v_pk_fma_f32 v[98:99], s[60:61], v[98:99], v[104:105]
	v_mul_f32_e32 v105, v101, v101
	v_mul_f32_e32 v104, v99, v99
	v_fmac_f32_e32 v104, v98, v98
	v_fmac_f32_e32 v105, v100, v100
	v_add_f32_e32 v104, v104, v105
	v_add_f32_e32 v106, v104, v110
	v_cvt_pk_bf16_f32 v104, v98, v99
	ds_bpermute_b32 v98, v116, v106
	v_cvt_pk_bf16_f32 v105, v100, v101
	global_store_dwordx4 v[114:115], v[102:105], off offset:256
	s_waitcnt lgkmcnt(0)
	v_add_f32_e32 v98, v106, v98
	ds_bpermute_b32 v99, v117, v98
	s_and_saveexec_b64 s[44:45], vcc
	s_cbranch_execz .LBB0_527
	s_waitcnt lgkmcnt(0)
	v_add_f32_e32 v98, v98, v99
	ds_write_b32 v0, v98 offset:64
.LBB0_527:
	s_or_b64 exec, exec, s[44:45]
	v_or_b32_e32 v98, 32, v132
	s_waitcnt lgkmcnt(0)
	v_ashrrev_i32_e32 v99, 31, v98
	v_lshlrev_b64 v[98:99], 11, v[98:99]
	v_lshl_add_u64 v[98:99], s[28:29], 0, v[98:99]
	v_lshl_add_u64 v[98:99], v[130:131], 1, v[98:99]
	s_waitcnt vmcnt(15)
	v_mov_b32_e32 v100, v188
	v_mov_b32_e32 v101, v189
	v_mov_b32_e32 v102, v190
	v_mov_b32_e32 v103, v191
	s_nop 0
	v_lshlrev_b32_e32 v104, 16, v100
	v_and_b32_e32 v105, 0xffff0000, v100
	v_lshlrev_b32_e32 v100, 16, v101
	v_and_b32_e32 v101, 0xffff0000, v101
	v_pk_fma_f32 v[96:97], s[66:67], v[96:97], v[100:101]
	v_pk_fma_f32 v[94:95], s[60:61], v[94:95], v[104:105]
	v_mul_f32_e32 v101, v97, v97
	v_mul_f32_e32 v100, v95, v95
	v_fmac_f32_e32 v100, v94, v94
	v_fmac_f32_e32 v101, v96, v96
	v_add_f32_e32 v104, v100, v101
	v_cvt_pk_bf16_f32 v94, v94, v95
	v_cvt_pk_bf16_f32 v95, v96, v97
	v_lshlrev_b32_e32 v96, 16, v102
	v_and_b32_e32 v97, 0xffff0000, v102
	v_lshlrev_b32_e32 v100, 16, v103
	v_and_b32_e32 v101, 0xffff0000, v103
	v_pk_fma_f32 v[92:93], s[66:67], v[92:93], v[100:101]
	v_pk_fma_f32 v[90:91], s[60:61], v[90:91], v[96:97]
	v_mul_f32_e32 v97, v93, v93
	v_mul_f32_e32 v96, v91, v91
	v_fmac_f32_e32 v96, v90, v90
	v_fmac_f32_e32 v97, v92, v92
	v_add_f32_e32 v96, v96, v97
	v_add_f32_e32 v100, v104, v96
	v_cvt_pk_bf16_f32 v96, v90, v91
	v_cvt_pk_bf16_f32 v97, v92, v93
	s_waitcnt vmcnt(14)
	v_mov_b32_e32 v90, v216
	v_mov_b32_e32 v91, v217
	v_mov_b32_e32 v92, v218
	v_mov_b32_e32 v93, v219
	s_nop 0
	global_store_dwordx4 v[98:99], v[94:97], off
	s_nop 0
	s_nop 0
	v_lshlrev_b32_e32 v94, 16, v90
	v_and_b32_e32 v95, 0xffff0000, v90
	v_lshlrev_b32_e32 v90, 16, v91
	v_and_b32_e32 v91, 0xffff0000, v91
	v_pk_fma_f32 v[88:89], s[66:67], v[88:89], v[90:91]
	v_pk_fma_f32 v[86:87], s[60:61], v[86:87], v[94:95]
	v_mul_f32_e32 v91, v89, v89
	v_mul_f32_e32 v90, v87, v87
	v_fmac_f32_e32 v90, v86, v86
	v_fmac_f32_e32 v91, v88, v88
	v_add_f32_e32 v90, v90, v91
	v_add_f32_e32 v94, v100, v90
	v_cvt_pk_bf16_f32 v86, v86, v87
	v_cvt_pk_bf16_f32 v87, v88, v89
	v_lshlrev_b32_e32 v88, 16, v92
	v_and_b32_e32 v89, 0xffff0000, v92
	v_lshlrev_b32_e32 v90, 16, v93
	v_and_b32_e32 v91, 0xffff0000, v93
	v_pk_fma_f32 v[84:85], s[66:67], v[84:85], v[90:91]
	v_pk_fma_f32 v[82:83], s[60:61], v[82:83], v[88:89]
	v_mul_f32_e32 v89, v85, v85
	v_mul_f32_e32 v88, v83, v83
	v_fmac_f32_e32 v88, v82, v82
	v_fmac_f32_e32 v89, v84, v84
	v_add_f32_e32 v88, v88, v89
	v_add_f32_e32 v90, v88, v94
	v_cvt_pk_bf16_f32 v88, v82, v83
	ds_bpermute_b32 v82, v116, v90
	v_cvt_pk_bf16_f32 v89, v84, v85
	global_store_dwordx4 v[98:99], v[86:89], off offset:256
	s_waitcnt lgkmcnt(0)
	v_add_f32_e32 v82, v90, v82
	ds_bpermute_b32 v83, v117, v82
	s_and_saveexec_b64 s[44:45], vcc
	s_cbranch_execz .LBB0_529
	s_waitcnt lgkmcnt(0)
	v_add_f32_e32 v82, v82, v83
	ds_write_b32 v0, v82 offset:128
; DI u32x2 pk4(f32x4 v) { u32x2 r; r.x = cvt_pk(v[0], v[1]); r.y = cvt_pk(v[2], v[3]); return r; }
; DI void gemm_phase(LAS unsigned char* lds, const GemmDesc& d, float* __restrict__ X) {
;     ...
;           const int row = pm * 256 + 128 * ai + 16 * m + rb; float ss = 0.f;
; #pragma unroll
;           for (int bj = 0; bj < 2; ++bj) {
;             const size_t o = (size_t)row * DM + pn * 256 + 128 * bj + cb;
;             const u32x4 xw = *(const u32x4*)(d.O0 + o); u32x4 ow;
; #pragma unroll
;             for (int n = 0; n < 2; ++n) {
;               const unsigned w0 = n ? xw.z : xw.x, w1 = n ? xw.w : xw.y;
;               f32x4 xo; xo[0] = __uint_as_float(w0 << 16); xo[1] = __uint_as_float(w0 & 0xffff0000u); xo[2] = __uint_as_float(w1 << 16); xo[3] = __uint_as_float(w1 & 0xffff0000u);
;               const f32x4 xn = xo + acc[ai][bj][m][n] * alpha;
;               ss += (xn[0] * xn[0] + xn[1] * xn[1]) + (xn[2] * xn[2] + xn[3] * xn[3]);
;               const u32x2 pw = pk4(xn); if (n) { ow.z = pw.x; ow.w = pw.y; } else { ow.x = pw.x; ow.y = pw.y; }
;             }
;             *(u32x4*)(d.O0 + o) = ow;
;           }
;           ss += __shfl_xor(ss, 16); ss += __shfl_xor(ss, 32);
;           if (fq == 0) red[wc * 256 + 128 * ai + 16 * m + rb] = ss;
.LBB0_529:
	s_or_b64 exec, exec, s[44:45]
	v_or_b32_e32 v82, 48, v132
	s_waitcnt lgkmcnt(0)
	v_ashrrev_i32_e32 v83, 31, v82
	v_lshlrev_b64 v[82:83], 11, v[82:83]
	v_lshl_add_u64 v[82:83], s[28:29], 0, v[82:83]
	v_lshl_add_u64 v[82:83], v[130:131], 1, v[82:83]
	s_waitcnt vmcnt(15)
	v_mov_b32_e32 v84, v222
	v_mov_b32_e32 v85, v223
	v_mov_b32_e32 v86, v224
	v_mov_b32_e32 v87, v225
	s_nop 0
	v_lshlrev_b32_e32 v88, 16, v84
	v_and_b32_e32 v89, 0xffff0000, v84
	v_lshlrev_b32_e32 v84, 16, v85
	v_and_b32_e32 v85, 0xffff0000, v85
	v_pk_fma_f32 v[80:81], s[66:67], v[80:81], v[84:85]
	v_pk_fma_f32 v[78:79], s[60:61], v[78:79], v[88:89]
	v_mul_f32_e32 v85, v81, v81
	v_mul_f32_e32 v84, v79, v79
	v_fmac_f32_e32 v84, v78, v78
	v_fmac_f32_e32 v85, v80, v80
	v_add_f32_e32 v88, v84, v85
	v_cvt_pk_bf16_f32 v78, v78, v79
	v_cvt_pk_bf16_f32 v79, v80, v81
	v_lshlrev_b32_e32 v80, 16, v86
	v_and_b32_e32 v81, 0xffff0000, v86
	v_lshlrev_b32_e32 v84, 16, v87
	v_and_b32_e32 v85, 0xffff0000, v87
	v_pk_fma_f32 v[76:77], s[66:67], v[76:77], v[84:85]
	v_pk_fma_f32 v[74:75], s[60:61], v[74:75], v[80:81]
	v_mul_f32_e32 v81, v77, v77
	v_mul_f32_e32 v80, v75, v75
	v_fmac_f32_e32 v80, v74, v74
	v_fmac_f32_e32 v81, v76, v76
	v_add_f32_e32 v80, v80, v81
	v_add_f32_e32 v84, v88, v80
	v_cvt_pk_bf16_f32 v80, v74, v75
	v_cvt_pk_bf16_f32 v81, v76, v77
	s_waitcnt vmcnt(14)
	v_mov_b32_e32 v74, v226
	v_mov_b32_e32 v75, v227
	v_mov_b32_e32 v76, v228
	v_mov_b32_e32 v77, v229
	s_nop 0
	global_store_dwordx4 v[82:83], v[78:81], off
	s_nop 0
	s_nop 0
	v_lshlrev_b32_e32 v78, 16, v74
	v_and_b32_e32 v79, 0xffff0000, v74
	v_lshlrev_b32_e32 v74, 16, v75
	v_and_b32_e32 v75, 0xffff0000, v75
	v_pk_fma_f32 v[72:73], s[66:67], v[72:73], v[74:75]
	v_pk_fma_f32 v[70:71], s[60:61], v[70:71], v[78:79]
	v_mul_f32_e32 v75, v73, v73
	v_mul_f32_e32 v74, v71, v71
	v_fmac_f32_e32 v74, v70, v70
	v_fmac_f32_e32 v75, v72, v72
	v_add_f32_e32 v74, v74, v75
	v_add_f32_e32 v78, v84, v74
	v_cvt_pk_bf16_f32 v70, v70, v71
	v_cvt_pk_bf16_f32 v71, v72, v73
	v_lshlrev_b32_e32 v72, 16, v76
	v_and_b32_e32 v73, 0xffff0000, v76
	v_lshlrev_b32_e32 v74, 16, v77
	v_and_b32_e32 v75, 0xffff0000, v77
	v_pk_fma_f32 v[68:69], s[66:67], v[68:69], v[74:75]
	v_pk_fma_f32 v[66:67], s[60:61], v[66:67], v[72:73]
	v_mul_f32_e32 v73, v69, v69
	v_mul_f32_e32 v72, v67, v67
	v_fmac_f32_e32 v72, v66, v66
	v_fmac_f32_e32 v73, v68, v68
	v_add_f32_e32 v72, v72, v73
	v_add_f32_e32 v74, v72, v78
	v_cvt_pk_bf16_f32 v72, v66, v67
	ds_bpermute_b32 v66, v116, v74
	v_cvt_pk_bf16_f32 v73, v68, v69
	global_store_dwordx4 v[82:83], v[70:73], off offset:256
	s_waitcnt lgkmcnt(0)
	v_add_f32_e32 v66, v74, v66
	ds_bpermute_b32 v67, v117, v66
	s_and_saveexec_b64 s[44:45], vcc
	s_cbranch_execz .LBB0_531
	s_waitcnt lgkmcnt(0)
	v_add_f32_e32 v66, v66, v67
	ds_write_b32 v0, v66 offset:192
.LBB0_531:
	s_or_b64 exec, exec, s[44:45]
	v_add_u32_e32 v66, 0x80, v132
	s_waitcnt lgkmcnt(0)
	v_ashrrev_i32_e32 v67, 31, v66
	v_lshlrev_b64 v[66:67], 11, v[66:67]
	v_lshl_add_u64 v[66:67], s[28:29], 0, v[66:67]
	v_lshl_add_u64 v[66:67], v[130:131], 1, v[66:67]
	s_waitcnt vmcnt(15)
	v_mov_b32_e32 v68, v230
	v_mov_b32_e32 v69, v231
	v_mov_b32_e32 v70, v232
	v_mov_b32_e32 v71, v233
	s_nop 0
	v_lshlrev_b32_e32 v72, 16, v68
	v_and_b32_e32 v73, 0xffff0000, v68
	v_lshlrev_b32_e32 v68, 16, v69
	v_and_b32_e32 v69, 0xffff0000, v69
	v_pk_fma_f32 v[64:65], s[66:67], v[64:65], v[68:69]
	v_pk_fma_f32 v[62:63], s[60:61], v[62:63], v[72:73]
	v_mul_f32_e32 v69, v65, v65
	v_mul_f32_e32 v68, v63, v63
	v_fmac_f32_e32 v68, v62, v62
	v_fmac_f32_e32 v69, v64, v64
	v_add_f32_e32 v72, v68, v69
	v_cvt_pk_bf16_f32 v62, v62, v63
	v_cvt_pk_bf16_f32 v63, v64, v65
	v_lshlrev_b32_e32 v64, 16, v70
	v_and_b32_e32 v65, 0xffff0000, v70
	v_lshlrev_b32_e32 v68, 16, v71
	v_and_b32_e32 v69, 0xffff0000, v71
	v_pk_fma_f32 v[60:61], s[66:67], v[60:61], v[68:69]
	v_pk_fma_f32 v[58:59], s[60:61], v[58:59], v[64:65]
	v_mul_f32_e32 v65, v61, v61
	v_mul_f32_e32 v64, v59, v59
	v_fmac_f32_e32 v64, v58, v58
	v_fmac_f32_e32 v65, v60, v60
	v_add_f32_e32 v64, v64, v65
	v_add_f32_e32 v68, v72, v64
	v_cvt_pk_bf16_f32 v64, v58, v59
	v_cvt_pk_bf16_f32 v65, v60, v61
	s_waitcnt vmcnt(14)
	v_mov_b32_e32 v58, v234
	v_mov_b32_e32 v59, v235
	v_mov_b32_e32 v60, v236
	v_mov_b32_e32 v61, v237
	s_nop 0
	global_store_dwordx4 v[66:67], v[62:65], off
	s_nop 0
	s_nop 0
	v_lshlrev_b32_e32 v62, 16, v58
	v_and_b32_e32 v63, 0xffff0000, v58
	v_lshlrev_b32_e32 v58, 16, v59
	v_and_b32_e32 v59, 0xffff0000, v59
	v_pk_fma_f32 v[56:57], s[66:67], v[56:57], v[58:59]
	v_pk_fma_f32 v[54:55], s[60:61], v[54:55], v[62:63]
	v_mul_f32_e32 v59, v57, v57
	v_mul_f32_e32 v58, v55, v55
	v_fmac_f32_e32 v58, v54, v54
	v_fmac_f32_e32 v59, v56, v56
	v_add_f32_e32 v58, v58, v59
	v_add_f32_e32 v62, v68, v58
	v_cvt_pk_bf16_f32 v54, v54, v55
	v_cvt_pk_bf16_f32 v55, v56, v57
	v_lshlrev_b32_e32 v56, 16, v60
	v_and_b32_e32 v57, 0xffff0000, v60
	v_lshlrev_b32_e32 v58, 16, v61
	v_and_b32_e32 v59, 0xffff0000, v61
	v_pk_fma_f32 v[52:53], s[66:67], v[52:53], v[58:59]
	v_pk_fma_f32 v[50:51], s[60:61], v[50:51], v[56:57]
	v_mul_f32_e32 v57, v53, v53
	v_mul_f32_e32 v56, v51, v51
	v_fmac_f32_e32 v56, v50, v50
	v_fmac_f32_e32 v57, v52, v52
	v_add_f32_e32 v56, v56, v57
	v_add_f32_e32 v58, v56, v62
	v_cvt_pk_bf16_f32 v56, v50, v51
	ds_bpermute_b32 v50, v116, v58
	v_cvt_pk_bf16_f32 v57, v52, v53
	global_store_dwordx4 v[66:67], v[54:57], off offset:256
	s_waitcnt lgkmcnt(0)
	v_add_f32_e32 v50, v58, v50
	ds_bpermute_b32 v51, v117, v50
	s_and_saveexec_b64 s[44:45], vcc
	s_cbranch_execz .LBB0_533
	s_waitcnt lgkmcnt(0)
	v_add_f32_e32 v50, v50, v51
	ds_write_b32 v0, v50 offset:512
; DI u32x2 pk4(f32x4 v) { u32x2 r; r.x = cvt_pk(v[0], v[1]); r.y = cvt_pk(v[2], v[3]); return r; }
; DI void gemm_phase(LAS unsigned char* lds, const GemmDesc& d, float* __restrict__ X) {
;     ...
;           const int row = pm * 256 + 128 * ai + 16 * m + rb; float ss = 0.f;
; #pragma unroll
;           for (int bj = 0; bj < 2; ++bj) {
;             const size_t o = (size_t)row * DM + pn * 256 + 128 * bj + cb;
;             const u32x4 xw = *(const u32x4*)(d.O0 + o); u32x4 ow;
; #pragma unroll
;             for (int n = 0; n < 2; ++n) {
;               const unsigned w0 = n ? xw.z : xw.x, w1 = n ? xw.w : xw.y;
;               f32x4 xo; xo[0] = __uint_as_float(w0 << 16); xo[1] = __uint_as_float(w0 & 0xffff0000u); xo[2] = __uint_as_float(w1 << 16); xo[3] = __uint_as_float(w1 & 0xffff0000u);
;               const f32x4 xn = xo + acc[ai][bj][m][n] * alpha;
;               ss += (xn[0] * xn[0] + xn[1] * xn[1]) + (xn[2] * xn[2] + xn[3] * xn[3]);
;               const u32x2 pw = pk4(xn); if (n) { ow.z = pw.x; ow.w = pw.y; } else { ow.x = pw.x; ow.y = pw.y; }
;             }
;             *(u32x4*)(d.O0 + o) = ow;
;           }
;           ss += __shfl_xor(ss, 16); ss += __shfl_xor(ss, 32);
;           if (fq == 0) red[wc * 256 + 128 * ai + 16 * m + rb] = ss;
.LBB0_533:
	s_or_b64 exec, exec, s[44:45]
	v_add_u32_e32 v50, 0x90, v132
	s_waitcnt lgkmcnt(0)
	v_ashrrev_i32_e32 v51, 31, v50
	v_lshlrev_b64 v[50:51], 11, v[50:51]
	v_lshl_add_u64 v[50:51], s[28:29], 0, v[50:51]
	v_lshl_add_u64 v[50:51], v[130:131], 1, v[50:51]
	s_waitcnt vmcnt(15)
	v_mov_b32_e32 v52, v244
	v_mov_b32_e32 v53, v245
	v_mov_b32_e32 v54, v246
	v_mov_b32_e32 v55, v247
	s_nop 0
	v_lshlrev_b32_e32 v56, 16, v52
	v_and_b32_e32 v57, 0xffff0000, v52
	v_lshlrev_b32_e32 v52, 16, v53
	v_and_b32_e32 v53, 0xffff0000, v53
	v_pk_fma_f32 v[48:49], s[66:67], v[48:49], v[52:53]
	v_pk_fma_f32 v[46:47], s[60:61], v[46:47], v[56:57]
	v_mul_f32_e32 v53, v49, v49
	v_mul_f32_e32 v52, v47, v47
	v_fmac_f32_e32 v52, v46, v46
	v_fmac_f32_e32 v53, v48, v48
	v_add_f32_e32 v56, v52, v53
	v_cvt_pk_bf16_f32 v46, v46, v47
	v_cvt_pk_bf16_f32 v47, v48, v49
	v_lshlrev_b32_e32 v48, 16, v54
	v_and_b32_e32 v49, 0xffff0000, v54
	v_lshlrev_b32_e32 v52, 16, v55
	v_and_b32_e32 v53, 0xffff0000, v55
	v_pk_fma_f32 v[44:45], s[66:67], v[44:45], v[52:53]
	v_pk_fma_f32 v[42:43], s[60:61], v[42:43], v[48:49]
	v_mul_f32_e32 v49, v45, v45
	v_mul_f32_e32 v48, v43, v43
	v_fmac_f32_e32 v48, v42, v42
	v_fmac_f32_e32 v49, v44, v44
	v_add_f32_e32 v48, v48, v49
	v_add_f32_e32 v52, v56, v48
	v_cvt_pk_bf16_f32 v48, v42, v43
	v_cvt_pk_bf16_f32 v49, v44, v45
	s_waitcnt vmcnt(14)
	v_mov_b32_e32 v42, v248
	v_mov_b32_e32 v43, v249
	v_mov_b32_e32 v44, v250
	v_mov_b32_e32 v45, v251
	s_nop 0
	global_store_dwordx4 v[50:51], v[46:49], off
	s_nop 0
	s_nop 0
	v_lshlrev_b32_e32 v46, 16, v42
	v_and_b32_e32 v47, 0xffff0000, v42
	v_lshlrev_b32_e32 v42, 16, v43
	v_and_b32_e32 v43, 0xffff0000, v43
	v_pk_fma_f32 v[40:41], s[66:67], v[40:41], v[42:43]
	v_pk_fma_f32 v[38:39], s[60:61], v[38:39], v[46:47]
	v_mul_f32_e32 v43, v41, v41
	v_mul_f32_e32 v42, v39, v39
	v_fmac_f32_e32 v42, v38, v38
	v_fmac_f32_e32 v43, v40, v40
	v_add_f32_e32 v42, v42, v43
	v_add_f32_e32 v46, v52, v42
	v_cvt_pk_bf16_f32 v38, v38, v39
	v_cvt_pk_bf16_f32 v39, v40, v41
	v_lshlrev_b32_e32 v40, 16, v44
	v_and_b32_e32 v41, 0xffff0000, v44
	v_lshlrev_b32_e32 v42, 16, v45
	v_and_b32_e32 v43, 0xffff0000, v45
	v_pk_fma_f32 v[36:37], s[66:67], v[36:37], v[42:43]
	v_pk_fma_f32 v[34:35], s[60:61], v[34:35], v[40:41]
	v_mul_f32_e32 v41, v37, v37
	v_mul_f32_e32 v40, v35, v35
	v_fmac_f32_e32 v40, v34, v34
	v_fmac_f32_e32 v41, v36, v36
	v_add_f32_e32 v40, v40, v41
	v_add_f32_e32 v42, v40, v46
	v_cvt_pk_bf16_f32 v40, v34, v35
	ds_bpermute_b32 v34, v116, v42
	v_cvt_pk_bf16_f32 v41, v36, v37
	global_store_dwordx4 v[50:51], v[38:41], off offset:256
	s_waitcnt lgkmcnt(0)
	v_add_f32_e32 v34, v42, v34
	ds_bpermute_b32 v35, v117, v34
	s_and_saveexec_b64 s[44:45], vcc
	s_cbranch_execz .LBB0_535
	s_waitcnt lgkmcnt(0)
	v_add_f32_e32 v34, v34, v35
	ds_write_b32 v0, v34 offset:576
; DI u32x2 pk4(f32x4 v) { u32x2 r; r.x = cvt_pk(v[0], v[1]); r.y = cvt_pk(v[2], v[3]); return r; }
; DI void gemm_phase(LAS unsigned char* lds, const GemmDesc& d, float* __restrict__ X) {
;     ...
;           const int row = pm * 256 + 128 * ai + 16 * m + rb; float ss = 0.f;
; #pragma unroll
;           for (int bj = 0; bj < 2; ++bj) {
;             const size_t o = (size_t)row * DM + pn * 256 + 128 * bj + cb;
;             const u32x4 xw = *(const u32x4*)(d.O0 + o); u32x4 ow;
; #pragma unroll
;             for (int n = 0; n < 2; ++n) {
;               const unsigned w0 = n ? xw.z : xw.x, w1 = n ? xw.w : xw.y;
;               f32x4 xo; xo[0] = __uint_as_float(w0 << 16); xo[1] = __uint_as_float(w0 & 0xffff0000u); xo[2] = __uint_as_float(w1 << 16); xo[3] = __uint_as_float(w1 & 0xffff0000u);
;               const f32x4 xn = xo + acc[ai][bj][m][n] * alpha;
;               ss += (xn[0] * xn[0] + xn[1] * xn[1]) + (xn[2] * xn[2] + xn[3] * xn[3]);
;               const u32x2 pw = pk4(xn); if (n) { ow.z = pw.x; ow.w = pw.y; } else { ow.x = pw.x; ow.y = pw.y; }
;             }
;             *(u32x4*)(d.O0 + o) = ow;
;           }
;           ss += __shfl_xor(ss, 16); ss += __shfl_xor(ss, 32);
;           if (fq == 0) red[wc * 256 + 128 * ai + 16 * m + rb] = ss;
.LBB0_535:
	s_or_b64 exec, exec, s[44:45]
	v_add_u32_e32 v34, 0xa0, v132
	s_waitcnt lgkmcnt(0)
	v_ashrrev_i32_e32 v35, 31, v34
	v_lshlrev_b64 v[34:35], 11, v[34:35]
	v_lshl_add_u64 v[34:35], s[28:29], 0, v[34:35]
	v_lshl_add_u64 v[34:35], v[130:131], 1, v[34:35]
	s_waitcnt vmcnt(15)
	v_mov_b32_e32 v36, v142
	v_mov_b32_e32 v37, v143
	v_mov_b32_e32 v38, v144
	v_mov_b32_e32 v39, v145
	s_nop 0
	v_lshlrev_b32_e32 v40, 16, v36
	v_and_b32_e32 v41, 0xffff0000, v36
	v_lshlrev_b32_e32 v36, 16, v37
	v_and_b32_e32 v37, 0xffff0000, v37
	v_pk_fma_f32 v[32:33], s[66:67], v[32:33], v[36:37]
	v_pk_fma_f32 v[30:31], s[60:61], v[30:31], v[40:41]
	v_mul_f32_e32 v37, v33, v33
	v_mul_f32_e32 v36, v31, v31
	v_fmac_f32_e32 v36, v30, v30
	v_fmac_f32_e32 v37, v32, v32
	v_add_f32_e32 v40, v36, v37
	v_cvt_pk_bf16_f32 v30, v30, v31
	v_cvt_pk_bf16_f32 v31, v32, v33
	v_lshlrev_b32_e32 v32, 16, v38
	v_and_b32_e32 v33, 0xffff0000, v38
	v_lshlrev_b32_e32 v36, 16, v39
	v_and_b32_e32 v37, 0xffff0000, v39
	v_pk_fma_f32 v[28:29], s[66:67], v[28:29], v[36:37]
	v_pk_fma_f32 v[26:27], s[60:61], v[26:27], v[32:33]
	v_mul_f32_e32 v33, v29, v29
	v_mul_f32_e32 v32, v27, v27
	v_fmac_f32_e32 v32, v26, v26
	v_fmac_f32_e32 v33, v28, v28
	v_add_f32_e32 v32, v32, v33
	v_add_f32_e32 v36, v40, v32
	v_cvt_pk_bf16_f32 v32, v26, v27
	v_cvt_pk_bf16_f32 v33, v28, v29
	s_waitcnt vmcnt(14)
	v_mov_b32_e32 v26, v166
	v_mov_b32_e32 v27, v167
	v_mov_b32_e32 v28, v168
	v_mov_b32_e32 v29, v169
	s_nop 0
	global_store_dwordx4 v[34:35], v[30:33], off
	s_nop 0
	s_nop 0
	v_lshlrev_b32_e32 v30, 16, v26
	v_and_b32_e32 v31, 0xffff0000, v26
	v_lshlrev_b32_e32 v26, 16, v27
	v_and_b32_e32 v27, 0xffff0000, v27
	v_pk_fma_f32 v[24:25], s[66:67], v[24:25], v[26:27]
	v_pk_fma_f32 v[22:23], s[60:61], v[22:23], v[30:31]
	v_mul_f32_e32 v27, v25, v25
	v_mul_f32_e32 v26, v23, v23
	v_fmac_f32_e32 v26, v22, v22
	v_fmac_f32_e32 v27, v24, v24
	v_add_f32_e32 v26, v26, v27
	v_add_f32_e32 v30, v36, v26
	v_cvt_pk_bf16_f32 v22, v22, v23
	v_cvt_pk_bf16_f32 v23, v24, v25
	v_lshlrev_b32_e32 v24, 16, v28
	v_and_b32_e32 v25, 0xffff0000, v28
	v_lshlrev_b32_e32 v26, 16, v29
	v_and_b32_e32 v27, 0xffff0000, v29
	v_pk_fma_f32 v[20:21], s[66:67], v[20:21], v[26:27]
	v_pk_fma_f32 v[18:19], s[60:61], v[18:19], v[24:25]
	v_mul_f32_e32 v25, v21, v21
	v_mul_f32_e32 v24, v19, v19
	v_fmac_f32_e32 v24, v18, v18
	v_fmac_f32_e32 v25, v20, v20
	v_add_f32_e32 v24, v24, v25
	v_add_f32_e32 v26, v24, v30
	v_cvt_pk_bf16_f32 v24, v18, v19
	ds_bpermute_b32 v18, v116, v26
	v_cvt_pk_bf16_f32 v25, v20, v21
	global_store_dwordx4 v[34:35], v[22:25], off offset:256
	s_waitcnt lgkmcnt(0)
	v_add_f32_e32 v18, v26, v18
	ds_bpermute_b32 v19, v117, v18
	s_and_saveexec_b64 s[44:45], vcc
	s_cbranch_execz .LBB0_537
	s_waitcnt lgkmcnt(0)
	v_add_f32_e32 v18, v18, v19
	ds_write_b32 v0, v18 offset:640
.LBB0_537:
	s_or_b64 exec, exec, s[44:45]
	v_add_u32_e32 v18, 0xb0, v132
	s_waitcnt lgkmcnt(0)
	v_ashrrev_i32_e32 v19, 31, v18
	v_lshlrev_b64 v[18:19], 11, v[18:19]
	v_lshl_add_u64 v[18:19], s[28:29], 0, v[18:19]
	v_lshl_add_u64 v[18:19], v[130:131], 1, v[18:19]
	s_waitcnt vmcnt(13)
	v_mov_b32_e32 v20, v170
	v_mov_b32_e32 v21, v171
	v_mov_b32_e32 v22, v172
	v_mov_b32_e32 v23, v173
	s_nop 0
	v_lshlrev_b32_e32 v24, 16, v20
	v_and_b32_e32 v25, 0xffff0000, v20
	v_lshlrev_b32_e32 v20, 16, v21
	v_and_b32_e32 v21, 0xffff0000, v21
	v_pk_fma_f32 v[16:17], s[66:67], v[16:17], v[20:21]
	v_pk_fma_f32 v[14:15], s[60:61], v[14:15], v[24:25]
	v_mul_f32_e32 v21, v17, v17
	v_mul_f32_e32 v20, v15, v15
	v_fmac_f32_e32 v20, v14, v14
	v_fmac_f32_e32 v21, v16, v16
	v_add_f32_e32 v24, v20, v21
	v_cvt_pk_bf16_f32 v14, v14, v15
	v_cvt_pk_bf16_f32 v15, v16, v17
	v_lshlrev_b32_e32 v16, 16, v22
	v_and_b32_e32 v17, 0xffff0000, v22
	v_lshlrev_b32_e32 v20, 16, v23
	v_and_b32_e32 v21, 0xffff0000, v23
	v_pk_fma_f32 v[12:13], s[66:67], v[12:13], v[20:21]
	v_pk_fma_f32 v[10:11], s[60:61], v[10:11], v[16:17]
	v_mul_f32_e32 v17, v13, v13
	v_mul_f32_e32 v16, v11, v11
	v_fmac_f32_e32 v16, v10, v10
	v_fmac_f32_e32 v17, v12, v12
	v_add_f32_e32 v16, v16, v17
	v_add_f32_e32 v20, v24, v16
	v_cvt_pk_bf16_f32 v16, v10, v11
	v_cvt_pk_bf16_f32 v17, v12, v13
	s_waitcnt vmcnt(12)
	v_mov_b32_e32 v10, v184
	v_mov_b32_e32 v11, v185
	v_mov_b32_e32 v12, v186
	v_mov_b32_e32 v13, v187
	s_nop 0
	global_store_dwordx4 v[18:19], v[14:17], off
	s_nop 0
	s_nop 0
	v_lshlrev_b32_e32 v14, 16, v10
	v_and_b32_e32 v15, 0xffff0000, v10
	v_lshlrev_b32_e32 v10, 16, v11
	v_and_b32_e32 v11, 0xffff0000, v11
	v_pk_fma_f32 v[8:9], s[66:67], v[8:9], v[10:11]
	v_pk_fma_f32 v[6:7], s[60:61], v[6:7], v[14:15]
	v_mul_f32_e32 v11, v9, v9
	v_mul_f32_e32 v10, v7, v7
	v_fmac_f32_e32 v10, v6, v6
	v_fmac_f32_e32 v11, v8, v8
	v_add_f32_e32 v10, v10, v11
	v_add_f32_e32 v14, v20, v10
	v_cvt_pk_bf16_f32 v6, v6, v7
	v_cvt_pk_bf16_f32 v7, v8, v9
	v_lshlrev_b32_e32 v8, 16, v12
	v_and_b32_e32 v9, 0xffff0000, v12
	v_lshlrev_b32_e32 v10, 16, v13
	v_and_b32_e32 v11, 0xffff0000, v13
	v_pk_fma_f32 v[4:5], s[66:67], v[4:5], v[10:11]
	v_pk_fma_f32 v[2:3], s[60:61], v[2:3], v[8:9]
	v_mul_f32_e32 v9, v5, v5
	v_mul_f32_e32 v8, v3, v3
	v_fmac_f32_e32 v8, v2, v2
	v_fmac_f32_e32 v9, v4, v4
	v_add_f32_e32 v8, v8, v9
	v_add_f32_e32 v10, v8, v14
	v_cvt_pk_bf16_f32 v8, v2, v3
	ds_bpermute_b32 v2, v116, v10
	v_cvt_pk_bf16_f32 v9, v4, v5
	global_store_dwordx4 v[18:19], v[6:9], off offset:256
	s_waitcnt lgkmcnt(0)
	v_add_f32_e32 v2, v10, v2
	ds_bpermute_b32 v3, v117, v2
	s_and_saveexec_b64 s[44:45], vcc
	s_cbranch_execz .LBB0_539
	s_waitcnt lgkmcnt(0)
	v_add_f32_e32 v2, v2, v3
	ds_write_b32 v0, v2 offset:704
